# sample-attention item: the new-key/value row and Q loads issued at item start with the cache loads (were two serial round trips after the copy)
# baseline (speedup 1.0000x reference)
.LBB0_732:
	s_cmpk_lt_i32 s81, 0x306
	s_cbranch_scc0 .Lrs_item
	s_mov_b64 s[12:13], s[0:1]
	s_add_i32 s4, s81, 0xfffffd7a
	s_add_i32 s10, s4, s75
	s_load_dwordx4 s[28:31], s[12:13], 0x10
	s_load_dwordx2 s[22:23], s[12:13], 0x40
	s_load_dwordx4 s[24:27], s[12:13], 0xc8
	s_ashr_i32 s11, s10, 31
	s_lshl_b64 s[10:11], s[10:11], 16
	s_waitcnt lgkmcnt(0)
	s_add_u32 s12, s28, s10
	s_waitcnt vmcnt(5)
	v_mov_b32_e32 v8, v236
	s_addc_u32 s13, s29, s11
	s_add_u32 s16, s30, s10
	v_ashrrev_i32_e32 v9, 31, v8
	s_addc_u32 s17, s31, s11
	v_lshlrev_b64 v[4:5], 4, v[8:9]
	s_waitcnt vmcnt(4)
	v_lshl_add_u64 v[12:13], s[12:13], 0, v[4:5]
	v_lshl_add_u64 v[10:11], s[16:17], 0, v[4:5]
	s_add_u32 s40, s24, s10
	s_addc_u32 s41, s25, s11
	s_add_u32 s42, s40, 0x41b5e00
	s_addc_u32 s43, s41, 0
	s_add_u32 s44, s40, 0x51b5e00
	s_addc_u32 s45, s41, 0
	v_and_b32_e32 v204, 31, v8
	v_lshlrev_b32_e32 v204, 4, v204
	v_mov_b32_e32 v205, 0
	v_mov_b32_e32 v206, s42
	v_mov_b32_e32 v207, s43
	v_mov_b32_e32 v208, s44
	v_mov_b32_e32 v209, s45
	v_cmp_gt_u32_e32 vcc, 32, v8
	s_nop 1
	v_cndmask_b32_e32 v206, v208, v206, vcc
	v_cndmask_b32_e32 v207, v209, v207, vcc
	v_lshl_add_u64 v[204:205], v[206:207], 0, v[204:205]
	v_cmp_gt_u32_e32 vcc, 64, v8
	s_and_saveexec_b64 s[20:21], vcc
	global_load_dwordx4 v[204:207], v[204:205], off
	s_mov_b64 exec, s[20:21]
	s_or_b32 s40, s4, 0x4000
	s_mul_i32 s41, s40, 0x600
	s_mul_hi_u32 s40, s40, 0x600
	s_add_u32 s42, s26, s41
	s_addc_u32 s43, s27, s40
	s_add_u32 s42, s42, 0x6a80000
	s_addc_u32 s43, s43, 0
	v_lshlrev_b32_e32 v208, 1, v8
	s_nop 3
	global_load_ushort v209, v208, s[42:43]
	global_load_dwordx4 v[116:119], v[12:13], off nt
	global_load_dwordx4 v[120:123], v[10:11], off nt
	v_add_co_u32_e32 v200, vcc, 0x2000, v12
	s_nop 1
	v_addc_co_u32_e32 v201, vcc, 0, v13, vcc
	v_add_co_u32_e32 v202, vcc, 0x2000, v10
	s_nop 1
	v_addc_co_u32_e32 v203, vcc, 0, v11, vcc
	global_load_dwordx4 v[124:127], v[200:201], off nt
	global_load_dwordx4 v[128:131], v[202:203], off nt
	v_add_co_u32_e32 v200, vcc, 0x4000, v12
	s_nop 1
	v_addc_co_u32_e32 v201, vcc, 0, v13, vcc
	v_add_co_u32_e32 v202, vcc, 0x4000, v10
	s_nop 1
	v_addc_co_u32_e32 v203, vcc, 0, v11, vcc
	global_load_dwordx4 v[132:135], v[200:201], off nt
	global_load_dwordx4 v[136:139], v[202:203], off nt
	v_add_co_u32_e32 v200, vcc, 0x6000, v12
	s_nop 1
	v_addc_co_u32_e32 v201, vcc, 0, v13, vcc
	v_add_co_u32_e32 v202, vcc, 0x6000, v10
	s_nop 1
	v_addc_co_u32_e32 v203, vcc, 0, v11, vcc
	global_load_dwordx4 v[140:143], v[200:201], off nt
	global_load_dwordx4 v[144:147], v[202:203], off nt
	v_add_co_u32_e32 v200, vcc, 0x8000, v12
	s_nop 1
	v_addc_co_u32_e32 v201, vcc, 0, v13, vcc
	v_add_co_u32_e32 v202, vcc, 0x8000, v10
	s_nop 1
	v_addc_co_u32_e32 v203, vcc, 0, v11, vcc
	global_load_dwordx4 v[148:151], v[200:201], off nt
	global_load_dwordx4 v[152:155], v[202:203], off nt
	v_add_co_u32_e32 v200, vcc, 0xa000, v12
	s_nop 1
	v_addc_co_u32_e32 v201, vcc, 0, v13, vcc
	v_add_co_u32_e32 v202, vcc, 0xa000, v10
	s_nop 1
	v_addc_co_u32_e32 v203, vcc, 0, v11, vcc
	global_load_dwordx4 v[156:159], v[200:201], off nt
	global_load_dwordx4 v[160:163], v[202:203], off nt
	v_add_co_u32_e32 v200, vcc, 0xc000, v12
	s_nop 1
	v_addc_co_u32_e32 v201, vcc, 0, v13, vcc
	v_add_co_u32_e32 v202, vcc, 0xc000, v10
	s_nop 1
	v_addc_co_u32_e32 v203, vcc, 0, v11, vcc
	global_load_dwordx4 v[184:187], v[200:201], off nt
	global_load_dwordx4 v[188:191], v[202:203], off nt
	v_add_co_u32_e32 v200, vcc, 0xe000, v12
	s_nop 1
	v_addc_co_u32_e32 v201, vcc, 0, v13, vcc
	v_add_co_u32_e32 v202, vcc, 0xe000, v10
	s_nop 1
	v_addc_co_u32_e32 v203, vcc, 0, v11, vcc
	global_load_dwordx4 v[192:195], v[200:201], off nt
	global_load_dwordx4 v[196:199], v[202:203], off nt
	s_add_u32 s10, s24, s10
	s_addc_u32 s11, s25, s11
	v_lshlrev_b32_e32 v14, 4, v8
	s_add_u32 s24, s10, 0x41a6000
	s_waitcnt vmcnt(19)
	v_ashrrev_i32_e32 v16, 5, v8
	v_and_b32_e32 v15, 0x1f0, v14
	s_addc_u32 s25, s11, 0
	s_waitcnt vmcnt(16)
	v_mul_lo_u32 v17, v16, s72
	v_add_u32_e32 v14, 0, v15
	v_readlane_b32 s12, v255, 52
	s_add_u32 s28, s10, 0x51a6000
	v_readfirstlane_b32 s16, v8
	v_add_u32_e32 v15, s12, v15
	v_add_u32_e32 v18, v14, v17
	s_addc_u32 s29, s11, 0
	v_cmp_lt_i32_e32 vcc, 0, v16
	v_add_u32_e32 v17, v15, v17
	s_waitcnt vmcnt(15)
	ds_write_b128 v18, v[116:119]
	s_waitcnt vmcnt(14)
	ds_write_b128 v17, v[120:123]
	s_and_saveexec_b64 s[10:11], vcc
	s_cbranch_execz .LBB0_734
	v_subrev_u32_e32 v174, 32, v8
	v_lshlrev_b64 v[16:17], 4, v[174:175]
	v_lshl_add_u64 v[18:19], s[24:25], 0, v[16:17]
	v_lshl_add_u64 v[16:17], s[28:29], 0, v[16:17]
	global_store_dwordx4 v[18:19], v[116:119], off nt
	global_store_dwordx4 v[16:17], v[120:123], off nt

.LBB0_748:
	s_or_b64 exec, exec, s[10:11]
	v_cmp_lt_i32_e32 vcc, 31, v8
	s_and_saveexec_b64 s[10:11], vcc
	s_xor_b64 s[10:11], exec, s[10:11]
	s_cbranch_execz .LBB0_752
	v_cmp_gt_u32_e32 vcc, 64, v8
	s_and_saveexec_b64 s[12:13], vcc
	s_cbranch_execz .LBB0_751
	v_lshl_add_u64 v[0:1], v[8:9], 4, s[28:29]
	v_add_co_u32_e32 v0, vcc, 0xf000, v0
	v_lshl_add_u32 v2, v8, 4, 0
	s_nop 0
	v_addc_co_u32_e32 v1, vcc, 0, v1, vcc
	v_add_u32_e32 v4, 0x21010, v2
	ds_write_b128 v4, v[204:207]

.LBB0_752:
	s_andn2_saveexec_b64 s[10:11], s[10:11]
	s_cbranch_execz .LBB0_754
	v_lshl_add_u64 v[0:1], v[8:9], 4, s[24:25]
	v_add_co_u32_e32 v0, vcc, 0xf000, v0
	v_lshl_add_u32 v4, v8, 4, 0
	s_nop 0
	v_addc_co_u32_e32 v1, vcc, 0, v1, vcc
	v_add_u32_e32 v4, 0x10800, v4
	ds_write_b128 v4, v[204:207]
.LBB0_754:
	s_or_b64 exec, exec, s[10:11]
	s_bitset1_b32 s4, 14
	s_ashr_i32 s10, s16, 6
	s_mul_i32 s12, s4, 0x600
	s_mul_hi_u32 s11, s4, 0x600
	s_add_u32 s12, s26, s12
	s_addc_u32 s13, s27, s11
	v_lshl_add_u64 v[0:1], v[8:9], 1, s[12:13]
	s_mov_b32 s11, 0x6a80000
	v_add_co_u32_e32 v0, vcc, s11, v0
	v_readlane_b32 s17, v255, 53
	s_nop 0
	v_addc_co_u32_e32 v1, vcc, 0, v1, vcc
	v_lshl_add_u32 v1, v8, 2, s17
	s_add_i32 s11, s10, 1
	v_and_b32_e32 v64, 63, v8
	v_mov_b32_e32 v0, v209
	v_lshlrev_b32_e32 v0, 16, v0
	ds_write_b32 v1, v0
	v_cvt_f32_i32_e32 v0, s11
	s_mov_b32 s11, 0x42fc0000
	s_waitcnt lgkmcnt(0)
	s_barrier
	v_cmp_lt_f32_e32 vcc, s11, v0
	s_and_b64 s[12:13], vcc, exec
	s_cselect_b32 s11, 0xffffffc0, 0
	v_cndmask_b32_e32 v1, 0, v242, vcc
	s_add_i32 s12, s10, s58
	v_sub_f32_e32 v0, v1, v0
	s_ashr_i32 s13, s12, 31
	v_exp_f32_e32 v0, v0
	s_lshl_b64 s[12:13], s[12:13], 2
	s_add_u32 s12, s22, s12
	s_addc_u32 s13, s23, s13
	global_load_dword v65, v175, s[12:13]
	s_and_b32 s12, s16, 0xffffff00
	s_and_b32 s24, s16, 0xffffffc0
	v_ldexp_f32 v0, v0, s11
	s_add_i32 s11, s12, 0
	s_lshl_b32 s13, s24, 2
	s_add_i32 s13, s17, s13
	v_mul_f32_e32 v66, 0x3fb8aa3b, v0
	v_mov_b32_e32 v0, s11
	v_mad_u32_u24 v67, v64, s72, v0
	v_mov_b32_e32 v44, s13
	ds_read_b128 v[12:15], v67
	ds_read_b128 v[16:19], v67 offset:16
	ds_read_b128 v[20:23], v67 offset:32
	ds_read_b128 v[24:27], v67 offset:48
	ds_read_b128 v[28:31], v44
	ds_read_b128 v[8:11], v44 offset:16
	ds_read_b128 v[4:7], v44 offset:32
	ds_read_b128 v[0:3], v44 offset:48
	s_add_i32 s13, s11, 0x10800
	s_waitcnt lgkmcnt(3)
	v_mul_f32_e32 v13, v13, v29
	v_fmac_f32_e32 v13, v12, v28
	v_mul_f32_e32 v12, v15, v31
	v_fmac_f32_e32 v12, v14, v30
	v_add_f32_e32 v12, v13, v12
	s_waitcnt lgkmcnt(2)
	v_mul_f32_e32 v13, v17, v9
	v_mul_f32_e32 v14, v19, v11
	v_fmac_f32_e32 v13, v16, v8
	v_fmac_f32_e32 v14, v18, v10
	v_add_f32_e32 v12, 0, v12
	v_add_f32_e32 v13, v13, v14
	v_add_f32_e32 v12, v12, v13
	s_waitcnt lgkmcnt(1)
	v_mul_f32_e32 v13, v21, v5
	v_mul_f32_e32 v14, v23, v7
	v_fmac_f32_e32 v13, v20, v4
	v_fmac_f32_e32 v14, v22, v6
	v_add_f32_e32 v13, v13, v14
	v_add_f32_e32 v12, v12, v13
	s_waitcnt lgkmcnt(0)
	v_mul_f32_e32 v13, v25, v1
	v_mul_f32_e32 v14, v27, v3
	v_fmac_f32_e32 v13, v24, v0
	v_fmac_f32_e32 v14, v26, v2
	v_add_f32_e32 v13, v13, v14
	v_add_f32_e32 v16, v12, v13
	ds_read_b128 v[12:15], v67 offset:64
	ds_read_b128 v[24:27], v44 offset:64
	v_cmp_eq_u32_e32 vcc, 0, v64
	s_waitcnt lgkmcnt(0)
	v_mul_f32_e32 v13, v13, v25
	v_fmac_f32_e32 v13, v12, v24
	v_mul_f32_e32 v12, v15, v27
	v_fmac_f32_e32 v12, v14, v26
	v_add_f32_e32 v12, v13, v12
	v_add_f32_e32 v20, v16, v12
	ds_read_b128 v[12:15], v67 offset:80
	ds_read_b128 v[16:19], v44 offset:80
	s_waitcnt lgkmcnt(0)
	v_mul_f32_e32 v13, v13, v17
	v_fmac_f32_e32 v13, v12, v16
	v_mul_f32_e32 v12, v15, v19
	v_fmac_f32_e32 v12, v14, v18
	v_add_f32_e32 v12, v13, v12
	v_add_f32_e32 v32, v20, v12
	ds_read_b128 v[12:15], v67 offset:96
	ds_read_b128 v[20:23], v44 offset:96
	s_waitcnt lgkmcnt(0)
	v_mul_f32_e32 v13, v13, v21
	v_fmac_f32_e32 v13, v12, v20
	v_mul_f32_e32 v12, v15, v23
	v_fmac_f32_e32 v12, v14, v22
	v_add_f32_e32 v12, v13, v12
	v_add_f32_e32 v36, v32, v12
	ds_read_b128 v[32:35], v67 offset:112
	ds_read_b128 v[12:15], v44 offset:112
	s_waitcnt lgkmcnt(0)
	v_mul_f32_e32 v33, v33, v13
	v_fmac_f32_e32 v33, v32, v12
	v_mul_f32_e32 v32, v35, v15
	v_fmac_f32_e32 v32, v34, v14
	v_add_f32_e32 v32, v33, v32
	v_add_f32_e32 v36, v36, v32
	ds_read_b128 v[32:35], v67 offset:128
	ds_read_b128 v[48:51], v44 offset:128
	s_waitcnt lgkmcnt(0)
	v_mul_f32_e32 v33, v33, v49
	v_fmac_f32_e32 v33, v32, v48
	v_mul_f32_e32 v32, v35, v51
	v_fmac_f32_e32 v32, v34, v50
	v_add_f32_e32 v32, v33, v32
	v_add_f32_e32 v40, v36, v32
	ds_read_b128 v[36:39], v67 offset:144
	ds_read_b128 v[32:35], v44 offset:144
	s_waitcnt lgkmcnt(0)
	v_mul_f32_e32 v37, v37, v33
	v_fmac_f32_e32 v37, v36, v32
	v_mul_f32_e32 v36, v39, v35
	v_fmac_f32_e32 v36, v38, v34
	v_add_f32_e32 v36, v37, v36
	v_add_f32_e32 v40, v40, v36
	ds_read_b128 v[36:39], v67 offset:160
	ds_read_b128 v[52:55], v44 offset:160
	s_waitcnt lgkmcnt(0)
	v_mul_f32_e32 v37, v37, v53
	v_fmac_f32_e32 v37, v36, v52
	v_mul_f32_e32 v36, v39, v55
	v_fmac_f32_e32 v36, v38, v54
	v_add_f32_e32 v36, v37, v36
	v_add_f32_e32 v45, v40, v36
	ds_read_b128 v[40:43], v67 offset:176
	ds_read_b128 v[36:39], v44 offset:176
	s_waitcnt lgkmcnt(0)
	v_mul_f32_e32 v41, v41, v37
	v_fmac_f32_e32 v41, v40, v36
	v_mul_f32_e32 v40, v43, v39
	v_fmac_f32_e32 v40, v42, v38
	v_add_f32_e32 v40, v41, v40
	v_add_f32_e32 v45, v45, v40
	ds_read_b128 v[40:43], v67 offset:192
	ds_read_b128 v[56:59], v44 offset:192
	s_waitcnt lgkmcnt(0)
	v_mul_f32_e32 v41, v41, v57
	v_fmac_f32_e32 v41, v40, v56
	v_mul_f32_e32 v40, v43, v59
	v_fmac_f32_e32 v40, v42, v58
	v_add_f32_e32 v40, v41, v40
	v_add_f32_e32 v45, v45, v40
	ds_read_b128 v[60:63], v67 offset:208
	ds_read_b128 v[40:43], v44 offset:208
	s_waitcnt lgkmcnt(0)
	v_mul_f32_e32 v46, v61, v41
	v_mul_f32_e32 v47, v63, v43
	v_fmac_f32_e32 v46, v60, v40
	v_fmac_f32_e32 v47, v62, v42
	ds_read_b128 v[68:71], v67 offset:224
	ds_read_b128 v[60:63], v44 offset:224
	v_add_f32_e32 v46, v46, v47
	v_add_f32_e32 v45, v45, v46
	s_waitcnt lgkmcnt(0)
	v_mul_f32_e32 v46, v69, v61
	v_mul_f32_e32 v47, v71, v63
	v_fmac_f32_e32 v46, v68, v60
	v_fmac_f32_e32 v47, v70, v62
	v_add_f32_e32 v46, v46, v47
	v_add_f32_e32 v72, v45, v46
	ds_read_b128 v[68:71], v67 offset:240
	ds_read_b128 v[44:47], v44 offset:240
	s_waitcnt lgkmcnt(0)
	v_mul_f32_e32 v69, v69, v45
	v_fmac_f32_e32 v69, v68, v44
	v_mul_f32_e32 v68, v71, v47
	v_fmac_f32_e32 v68, v70, v46
	v_add_f32_e32 v68, v69, v68
	v_add_f32_e32 v68, v72, v68
	ds_read_b128 v[70:73], v67 offset:33792
	v_sub_u32_e32 v69, 0x80, v64
	v_cvt_f32_ubyte0_e32 v69, v69
	v_fma_f32 v68, -v66, v69, v68
	v_or_b32_e32 v69, 64, v64
	s_waitcnt lgkmcnt(0)
	v_mul_f32_e32 v71, v29, v71
	v_fmac_f32_e32 v71, v28, v70
	v_mul_f32_e32 v70, v31, v73
	v_fmac_f32_e32 v70, v30, v72
	v_add_f32_e32 v70, v71, v70
	v_add_f32_e32 v74, 0, v70
	ds_read_b128 v[70:73], v67 offset:33808
	v_sub_u32_e32 v69, 0x80, v69
	v_cvt_f32_ubyte0_e32 v69, v69
	s_waitcnt lgkmcnt(0)
	v_mul_f32_e32 v71, v9, v71
	v_fmac_f32_e32 v71, v8, v70
	v_mul_f32_e32 v70, v11, v73
	v_fmac_f32_e32 v70, v10, v72
	v_add_f32_e32 v70, v71, v70
	v_add_f32_e32 v74, v74, v70
	ds_read_b128 v[70:73], v67 offset:33824
	s_waitcnt lgkmcnt(0)
	v_mul_f32_e32 v71, v5, v71
	v_fmac_f32_e32 v71, v4, v70
	v_mul_f32_e32 v70, v7, v73
	v_fmac_f32_e32 v70, v6, v72
	v_add_f32_e32 v70, v71, v70
	v_add_f32_e32 v74, v74, v70
	ds_read_b128 v[70:73], v67 offset:33840
	s_waitcnt lgkmcnt(0)
	v_mul_f32_e32 v71, v1, v71
	v_fmac_f32_e32 v71, v0, v70
	v_mul_f32_e32 v70, v3, v73
	v_fmac_f32_e32 v70, v2, v72
	v_add_f32_e32 v70, v71, v70
	v_add_f32_e32 v74, v74, v70
	ds_read_b128 v[70:73], v67 offset:33856
	s_waitcnt lgkmcnt(0)
	v_mul_f32_e32 v71, v25, v71
	v_fmac_f32_e32 v71, v24, v70
	v_mul_f32_e32 v70, v27, v73
	v_fmac_f32_e32 v70, v26, v72
	v_add_f32_e32 v70, v71, v70
	v_add_f32_e32 v74, v74, v70
	ds_read_b128 v[70:73], v67 offset:33872
	s_waitcnt lgkmcnt(0)
	v_mul_f32_e32 v71, v17, v71
	v_fmac_f32_e32 v71, v16, v70
	v_mul_f32_e32 v70, v19, v73
	v_fmac_f32_e32 v70, v18, v72
	v_add_f32_e32 v70, v71, v70
	v_add_f32_e32 v74, v74, v70
	ds_read_b128 v[70:73], v67 offset:33888
	s_waitcnt lgkmcnt(0)
	v_mul_f32_e32 v71, v21, v71
	v_fmac_f32_e32 v71, v20, v70
	v_mul_f32_e32 v70, v23, v73
	v_fmac_f32_e32 v70, v22, v72
	v_add_f32_e32 v70, v71, v70
	v_add_f32_e32 v74, v74, v70
	ds_read_b128 v[70:73], v67 offset:33904
	s_waitcnt lgkmcnt(0)
	v_mul_f32_e32 v71, v13, v71
	v_fmac_f32_e32 v71, v12, v70
	v_mul_f32_e32 v70, v15, v73
	v_fmac_f32_e32 v70, v14, v72
	v_add_f32_e32 v70, v71, v70
	v_add_f32_e32 v74, v74, v70
	ds_read_b128 v[70:73], v67 offset:33920
	s_waitcnt lgkmcnt(0)
	v_mul_f32_e32 v71, v49, v71
	v_fmac_f32_e32 v71, v48, v70
	v_mul_f32_e32 v70, v51, v73
	v_fmac_f32_e32 v70, v50, v72
	v_add_f32_e32 v70, v71, v70
	v_add_f32_e32 v74, v74, v70
	ds_read_b128 v[70:73], v67 offset:33936
	s_waitcnt lgkmcnt(0)
	v_mul_f32_e32 v71, v33, v71
	v_fmac_f32_e32 v71, v32, v70
	v_mul_f32_e32 v70, v35, v73
	v_fmac_f32_e32 v70, v34, v72
	v_add_f32_e32 v70, v71, v70
	v_add_f32_e32 v74, v74, v70
	ds_read_b128 v[70:73], v67 offset:33952
	s_waitcnt lgkmcnt(0)
	v_mul_f32_e32 v71, v53, v71
	v_fmac_f32_e32 v71, v52, v70
	v_mul_f32_e32 v70, v55, v73
	v_fmac_f32_e32 v70, v54, v72
	v_add_f32_e32 v70, v71, v70
	v_add_f32_e32 v74, v74, v70
	ds_read_b128 v[70:73], v67 offset:33968
	s_waitcnt lgkmcnt(0)
	v_mul_f32_e32 v71, v37, v71
	v_fmac_f32_e32 v71, v36, v70
	v_mul_f32_e32 v70, v39, v73
	v_fmac_f32_e32 v70, v38, v72
	v_add_f32_e32 v70, v71, v70
	v_add_f32_e32 v74, v74, v70
	ds_read_b128 v[70:73], v67 offset:33984
	s_waitcnt lgkmcnt(0)
	v_mul_f32_e32 v71, v57, v71
	v_fmac_f32_e32 v71, v56, v70
	v_mul_f32_e32 v70, v59, v73
	v_fmac_f32_e32 v70, v58, v72
	v_add_f32_e32 v70, v71, v70
	v_add_f32_e32 v74, v74, v70
	ds_read_b128 v[70:73], v67 offset:34000
	s_waitcnt lgkmcnt(0)
	v_mul_f32_e32 v71, v41, v71
	v_fmac_f32_e32 v71, v40, v70
	v_mul_f32_e32 v70, v43, v73
	v_fmac_f32_e32 v70, v42, v72
	v_add_f32_e32 v70, v71, v70
	v_add_f32_e32 v74, v74, v70
	ds_read_b128 v[70:73], v67 offset:34016
	s_waitcnt lgkmcnt(0)
	v_mul_f32_e32 v71, v61, v71
	v_fmac_f32_e32 v71, v60, v70
	v_mul_f32_e32 v70, v63, v73
	v_fmac_f32_e32 v70, v62, v72
	v_add_f32_e32 v70, v71, v70
	v_add_f32_e32 v74, v74, v70
	ds_read_b128 v[70:73], v67 offset:34032
	s_waitcnt lgkmcnt(0)
	v_mul_f32_e32 v67, v45, v71
	v_fmac_f32_e32 v67, v44, v70
	v_mul_f32_e32 v70, v47, v73
	v_fmac_f32_e32 v70, v46, v72
	v_add_f32_e32 v67, v67, v70
	v_add_f32_e32 v67, v74, v67
	v_fma_f32 v67, -v66, v69, v67
	v_mov_b32_e32 v69, s13
	ds_read_b128 v[70:73], v69
	s_add_i32 s13, s11, 0x10810
	s_waitcnt lgkmcnt(0)
	v_mul_f32_e32 v29, v29, v71
	v_fmac_f32_e32 v29, v28, v70
	v_mul_f32_e32 v28, v31, v73
	v_fmac_f32_e32 v28, v30, v72
	v_add_f32_e32 v28, v29, v28
	v_add_f32_e32 v69, 0, v28
	v_mov_b32_e32 v28, s13
	ds_read_b128 v[28:31], v28
	s_add_i32 s13, s11, 0x10820
	s_waitcnt lgkmcnt(0)
	v_mul_f32_e32 v9, v9, v29
	v_fmac_f32_e32 v9, v8, v28
	v_mul_f32_e32 v8, v11, v31
	v_fmac_f32_e32 v8, v10, v30
	v_add_f32_e32 v8, v9, v8
	v_add_f32_e32 v28, v69, v8
	v_mov_b32_e32 v8, s13
	ds_read_b128 v[8:11], v8
	s_add_i32 s13, s11, 0x10830
	s_waitcnt lgkmcnt(0)
	v_mul_f32_e32 v5, v5, v9
	v_fmac_f32_e32 v5, v4, v8
	v_mul_f32_e32 v4, v7, v11
	v_fmac_f32_e32 v4, v6, v10
	v_add_f32_e32 v4, v5, v4
	v_add_f32_e32 v8, v28, v4
	v_mov_b32_e32 v4, s13
	ds_read_b128 v[4:7], v4
	s_add_i32 s13, s11, 0x10840
	s_waitcnt lgkmcnt(0)
	v_mul_f32_e32 v1, v1, v5
	v_fmac_f32_e32 v1, v0, v4
	v_mul_f32_e32 v0, v3, v7
	v_fmac_f32_e32 v0, v2, v6
	v_add_f32_e32 v0, v1, v0
	v_add_f32_e32 v4, v8, v0
	v_mov_b32_e32 v0, s13
	ds_read_b128 v[0:3], v0
	s_add_i32 s13, s11, 0x10850
	s_waitcnt lgkmcnt(0)
	v_mul_f32_e32 v1, v25, v1
	v_fmac_f32_e32 v1, v24, v0
	v_mul_f32_e32 v0, v27, v3
	v_fmac_f32_e32 v0, v26, v2
	v_add_f32_e32 v0, v1, v0
	v_add_f32_e32 v4, v4, v0
	v_mov_b32_e32 v0, s13
	ds_read_b128 v[0:3], v0
	s_add_i32 s13, s11, 0x10860
	s_waitcnt lgkmcnt(0)
	v_mul_f32_e32 v1, v17, v1
	v_fmac_f32_e32 v1, v16, v0
	v_mul_f32_e32 v0, v19, v3
	v_fmac_f32_e32 v0, v18, v2
	v_add_f32_e32 v0, v1, v0
	v_add_f32_e32 v4, v4, v0
	v_mov_b32_e32 v0, s13
	ds_read_b128 v[0:3], v0
	s_add_i32 s13, s11, 0x10870
	s_waitcnt lgkmcnt(0)
	v_mul_f32_e32 v1, v21, v1
	v_fmac_f32_e32 v1, v20, v0
	v_mul_f32_e32 v0, v23, v3
	v_fmac_f32_e32 v0, v22, v2
	v_add_f32_e32 v0, v1, v0
	v_add_f32_e32 v4, v4, v0
	v_mov_b32_e32 v0, s13
	ds_read_b128 v[0:3], v0
	s_add_i32 s13, s11, 0x10880
	s_waitcnt lgkmcnt(0)
	v_mul_f32_e32 v1, v13, v1
	v_fmac_f32_e32 v1, v12, v0
	v_mul_f32_e32 v0, v15, v3
	v_fmac_f32_e32 v0, v14, v2
	v_add_f32_e32 v0, v1, v0
	v_add_f32_e32 v4, v4, v0
	v_mov_b32_e32 v0, s13
	ds_read_b128 v[0:3], v0
	s_add_i32 s13, s11, 0x10890
	s_waitcnt lgkmcnt(0)
	v_mul_f32_e32 v1, v49, v1
	v_fmac_f32_e32 v1, v48, v0
	v_mul_f32_e32 v0, v51, v3
	v_fmac_f32_e32 v0, v50, v2
	v_add_f32_e32 v0, v1, v0
	v_add_f32_e32 v4, v4, v0
	v_mov_b32_e32 v0, s13
	ds_read_b128 v[0:3], v0
	s_add_i32 s13, s11, 0x108a0
	s_waitcnt lgkmcnt(0)
	v_mul_f32_e32 v1, v33, v1
	v_fmac_f32_e32 v1, v32, v0
	v_mul_f32_e32 v0, v35, v3
	v_fmac_f32_e32 v0, v34, v2
	v_add_f32_e32 v0, v1, v0
	v_add_f32_e32 v4, v4, v0
	v_mov_b32_e32 v0, s13
	ds_read_b128 v[0:3], v0
	s_add_i32 s13, s11, 0x108b0
	s_waitcnt lgkmcnt(0)
	v_mul_f32_e32 v1, v53, v1
	v_fmac_f32_e32 v1, v52, v0
	v_mul_f32_e32 v0, v55, v3
	v_fmac_f32_e32 v0, v54, v2
	v_add_f32_e32 v0, v1, v0
	v_add_f32_e32 v4, v4, v0
	v_mov_b32_e32 v0, s13
	ds_read_b128 v[0:3], v0
	s_add_i32 s13, s11, 0x108c0
	s_waitcnt lgkmcnt(0)
	v_mul_f32_e32 v1, v37, v1
	v_fmac_f32_e32 v1, v36, v0
	v_mul_f32_e32 v0, v39, v3
	v_fmac_f32_e32 v0, v38, v2
	v_add_f32_e32 v0, v1, v0
	v_add_f32_e32 v4, v4, v0
	v_mov_b32_e32 v0, s13
	ds_read_b128 v[0:3], v0
	s_add_i32 s13, s11, 0x108d0
	s_waitcnt lgkmcnt(0)
	v_mul_f32_e32 v1, v57, v1
	v_fmac_f32_e32 v1, v56, v0
	v_mul_f32_e32 v0, v59, v3
	v_fmac_f32_e32 v0, v58, v2
	v_add_f32_e32 v0, v1, v0
	v_add_f32_e32 v4, v4, v0
	v_mov_b32_e32 v0, s13
	ds_read_b128 v[0:3], v0
	s_add_i32 s13, s11, 0x108e0
	s_add_i32 s11, s11, 0x108f0
	s_waitcnt lgkmcnt(0)
	v_mul_f32_e32 v1, v41, v1
	v_fmac_f32_e32 v1, v40, v0
	v_mul_f32_e32 v0, v43, v3
	v_fmac_f32_e32 v0, v42, v2
	v_add_f32_e32 v0, v1, v0
	v_add_f32_e32 v4, v4, v0
	v_mov_b32_e32 v0, s13
	ds_read_b128 v[0:3], v0
	s_mul_i32 s13, s10, 0x210
	s_add_i32 s16, s13, 0
	s_add_i32 s16, s16, 0x21420
	s_waitcnt lgkmcnt(0)
	v_mul_f32_e32 v1, v61, v1
	v_fmac_f32_e32 v1, v60, v0
	v_mul_f32_e32 v0, v63, v3
	v_fmac_f32_e32 v0, v62, v2
	v_add_f32_e32 v0, v1, v0
	v_add_f32_e32 v4, v4, v0
	v_mov_b32_e32 v0, s11
	ds_read_b128 v[0:3], v0
	s_waitcnt lgkmcnt(0)
	v_mul_f32_e32 v1, v45, v1
	v_fmac_f32_e32 v1, v44, v0
	v_mul_f32_e32 v0, v47, v3
	v_fmac_f32_e32 v0, v46, v2
	v_add_f32_e32 v0, v1, v0
	v_add_f32_e32 v0, v4, v0
	v_and_b32_e32 v3, 64, v237
	v_fmac_f32_e32 v0, 0x80000000, v66
	v_add_u32_e32 v3, 64, v3
	v_xor_b32_e32 v4, 1, v237
	v_cndmask_b32_e32 v2, v243, v0, vcc
	s_waitcnt vmcnt(0)
	v_mul_f32_e32 v0, 0x3fb8aa3b, v65
	v_cmp_lt_i32_e64 s[22:23], v4, v3
	v_max_f32_e32 v1, v2, v0
	v_max3_f32 v1, v68, v67, v1
	v_cndmask_b32_e64 v4, v237, v4, s[22:23]
	v_lshlrev_b32_e32 v5, 2, v4
	ds_bpermute_b32 v4, v5, v1
	s_waitcnt lgkmcnt(0)
	v_max_f32_e32 v4, v4, v4
	v_max_f32_e32 v1, v1, v4
	v_xor_b32_e32 v4, 2, v237
	v_cmp_lt_i32_e64 s[22:23], v4, v3
	s_nop 1
	v_cndmask_b32_e64 v4, v237, v4, s[22:23]
	v_lshlrev_b32_e32 v6, 2, v4
	ds_bpermute_b32 v4, v6, v1
	s_waitcnt lgkmcnt(0)
	v_max_f32_e32 v4, v4, v4
	v_max_f32_e32 v1, v1, v4
	v_xor_b32_e32 v4, 4, v237
	v_cmp_lt_i32_e64 s[22:23], v4, v3
	s_nop 1
	v_cndmask_b32_e64 v4, v237, v4, s[22:23]
	v_lshlrev_b32_e32 v7, 2, v4
	ds_bpermute_b32 v4, v7, v1
	s_waitcnt lgkmcnt(0)
	v_max_f32_e32 v4, v4, v4
	v_max_f32_e32 v1, v1, v4
	v_xor_b32_e32 v4, 8, v237
	v_cmp_lt_i32_e64 s[22:23], v4, v3
	s_nop 1
	v_cndmask_b32_e64 v4, v237, v4, s[22:23]
	v_lshlrev_b32_e32 v8, 2, v4
	ds_bpermute_b32 v4, v8, v1
	s_waitcnt lgkmcnt(0)
	v_max_f32_e32 v4, v4, v4
	v_max_f32_e32 v1, v1, v4
	v_xor_b32_e32 v4, 16, v237
	v_cmp_lt_i32_e64 s[22:23], v4, v3
	s_nop 1
	v_cndmask_b32_e64 v4, v237, v4, s[22:23]
	v_lshlrev_b32_e32 v9, 2, v4
	ds_bpermute_b32 v4, v9, v1
	s_waitcnt lgkmcnt(0)
	v_max_f32_e32 v4, v4, v4
	v_max_f32_e32 v1, v1, v4
	v_xor_b32_e32 v4, 32, v237
	v_cmp_lt_i32_e64 s[22:23], v4, v3
	s_nop 1
	v_cndmask_b32_e64 v3, v237, v4, s[22:23]
	v_lshlrev_b32_e32 v3, 2, v3
	ds_bpermute_b32 v4, v3, v1
	s_waitcnt lgkmcnt(0)
	v_max_f32_e32 v4, v4, v4
	v_max_f32_e32 v1, v1, v4
	v_sub_f32_e32 v4, v68, v1
	v_exp_f32_e32 v10, v4
	v_sub_f32_e32 v11, v67, v1
	v_exp_f32_e32 v11, v11
	v_sub_f32_e32 v2, v2, v1
	v_add_f32_e32 v4, 0, v10
	v_add_f32_e32 v12, v11, v4
	v_exp_f32_e32 v4, v2
	s_nop 0
	v_add_f32_e32 v2, v4, v12
	ds_bpermute_b32 v5, v5, v2
	s_waitcnt lgkmcnt(0)
	v_add_f32_e32 v2, v2, v5
	ds_bpermute_b32 v5, v6, v2
	s_waitcnt lgkmcnt(0)
	v_add_f32_e32 v2, v2, v5
	ds_bpermute_b32 v5, v7, v2
	s_waitcnt lgkmcnt(0)
	v_add_f32_e32 v2, v2, v5
	ds_bpermute_b32 v5, v8, v2
	s_waitcnt lgkmcnt(0)
	v_add_f32_e32 v2, v2, v5
	ds_bpermute_b32 v5, v9, v2
	s_waitcnt lgkmcnt(0)
	v_add_f32_e32 v2, v2, v5
	ds_bpermute_b32 v3, v3, v2
	v_lshl_add_u32 v5, v64, 2, s16
	ds_write2st64_b32 v5, v10, v11 offset1:1
	s_and_saveexec_b64 s[10:11], vcc
	v_mov_b32_e32 v5, s16
	ds_write_b32 v5, v4 offset:512
	s_or_b64 exec, exec, s[10:11]
	s_waitcnt lgkmcnt(0)
	s_add_i32 s10, s12, 0x10c20
	v_lshlrev_b32_e32 v4, 2, v64
	s_add_i32 s12, s12, 0x10a10
	v_add_u32_e32 v5, s10, v4
	v_add_u32_e32 v6, s12, v4
	v_mov_b32_e32 v7, 0
	s_movk_i32 s12, 0x80
	s_branch .LBB0_758
